# SGU epilogue u loads issued together; MoBA k-mean loop loads next past block while reducing the current one
# speedup vs baseline: 1.0167x; 1.0007x over previous
; #define LAS __attribute__((address_space(3)))
; __device__ __forceinline__ unsigned cvtpk(float lo, float hi) { f32x2_t v = {lo, hi}; bf16x2_t b = __builtin_convertvector(v, bf16x2_t); return __builtin_bit_cast(unsigned, b); }
; __device__ __forceinline__ float bflo(unsigned u) { return __uint_as_float(u << 16); }
; __device__ __forceinline__ float bfhi(unsigned u) { return __uint_as_float(u & 0xffff0000u); }
; __device__ __forceinline__ float geluf_(float x) { const float y = 0.7978845608028654f * (x + 0.044715f * x * x * x); return x * sigmoidf_(2.0f * y); }
; #define MFMA32(a, b, c) __builtin_amdgcn_mfma_f32_32x32x16_bf16((a), (b), (c), 0, 0, 0)
; __device__ __forceinline__ void sgu_item(LAS unsigned char* lds, const bf16* PROJ, bf16* MIX, const float* lg, const float* lb, const float* ws_, const float* bs_, int item, int tid) {
;     ...
;         for (int ks = 0; ks < 2 * (wt + 1); ++ks) { const int s0 = 16 * ks + 8 * hi;
;             const f32x4 w0 = *(const f32x4*)(wrow + s0), w1 = *(const f32x4*)(wrow + s0 + 4);
;             u32x4 pk; pk.x = cvtpk(s0 + 0 <= trow ? w0.x : 0.f, s0 + 1 <= trow ? w0.y : 0.f); pk.y = cvtpk(s0 + 2 <= trow ? w0.z : 0.f, s0 + 3 <= trow ? w0.w : 0.f);
;             pk.z = cvtpk(s0 + 4 <= trow ? w1.x : 0.f, s0 + 5 <= trow ? w1.y : 0.f); pk.w = cvtpk(s0 + 6 <= trow ? w1.z : 0.f, s0 + 7 <= trow ? w1.w : 0.f);
;             const bf16x8 wa = __builtin_bit_cast(bf16x8, pk);
; #pragma unroll
;             for (int ct = 0; ct < 2; ++ct) { const bf16x8 vb = *(LAS const bf16x8*)(vnT + (64 * wcg + 32 * ct + r32) * SGP + s0 * 2); acc[ct] = MFMA32(vb, wa, acc[ct]); } }
;         { const int t = 32 * wt + r32; const float bias = bs_[g * 128 + t]; const bf16* up = PROJ + (row0 + t) * NPROJ + 128 * g + 64 * wcg + 4 * hi; bf16* op = MIX + (row0 + t) * D + 128 * g + 64 * wcg + 4 * hi;
; #pragma unroll
;           for (int ct = 0; ct < 2; ++ct)
; #pragma unroll
;             for (int g4 = 0; g4 < 4; ++g4) { const u32x2 uw = *(const u32x2*)(up + 32 * ct + 8 * g4);
;                 const float o0 = geluf_(bflo(uw.x)) * (acc[ct][4 * g4] + bias), o1 = geluf_(bfhi(uw.x)) * (acc[ct][4 * g4 + 1] + bias), o2 = geluf_(bflo(uw.y)) * (acc[ct][4 * g4 + 2] + bias), o3 = geluf_(bfhi(uw.y)) * (acc[ct][4 * g4 + 3] + bias);
;                 u32x2 w; w.x = cvtpk(o0, o1); w.y = cvtpk(o2, o3); *(u32x2*)(op + 32 * ct + 8 * g4) = w; } }
.Lsgu_c_nopf:
	v_cndmask_b32_e32 v34, 0, v34, vcc
	v_cmp_lt_u32_e32 vcc, v40, v43
	s_nop 1
	v_cndmask_b32_e32 v35, 0, v35, vcc
	v_cvt_pk_bf16_f32 v34, v34, v35
	v_add_u32_e32 v35, 2, v40
	v_cmp_le_u32_e32 vcc, v35, v43
	s_nop 1
	v_cndmask_b32_e32 v35, 0, v36, vcc
	v_add_u32_e32 v36, 3, v40
	v_cmp_le_u32_e32 vcc, v36, v43
	s_nop 1
	v_cndmask_b32_e32 v36, 0, v37, vcc
	v_cvt_pk_bf16_f32 v35, v35, v36
	v_add_u32_e32 v36, 4, v40
	v_cmp_le_u32_e32 vcc, v36, v43
	v_add_u32_e32 v37, 5, v40
	s_nop 0
	v_cndmask_b32_e32 v36, 0, v54, vcc
	v_cmp_le_u32_e32 vcc, v37, v43
	s_nop 1
	v_cndmask_b32_e32 v37, 0, v55, vcc
	v_cvt_pk_bf16_f32 v36, v36, v37
	v_add_u32_e32 v37, 6, v40
	v_cmp_le_u32_e32 vcc, v37, v43
	v_add_u32_e32 v40, 7, v40
	s_nop 0
	v_cndmask_b32_e32 v37, 0, v56, vcc
	v_cmp_le_u32_e32 vcc, v40, v43
	s_nop 1
	v_cndmask_b32_e32 v40, 0, v57, vcc
	ds_read_b128 v[54:57], v0
	v_cvt_pk_bf16_f32 v37, v37, v40
	s_waitcnt lgkmcnt(0)
	s_nop 0
	v_mfma_f32_32x32x16_bf16 v[18:33], v[54:57], v[34:37], v[18:33]
	ds_read_b128 v[54:57], v0 offset:8704
	v_add_u32_e32 v0, 32, v0
	s_waitcnt lgkmcnt(0)
	v_mfma_f32_32x32x16_bf16 v[2:17], v[54:57], v[34:37], v[2:17]
	s_cbranch_scc0 .LBB0_364
	s_lshl_b32 s82, s2, 1
	v_lshl_add_u64 v[36:37], v[48:49], 0, s[82:83]
	global_load_dwordx2 v[116:117], v[36:37], off
	global_load_dwordx2 v[118:119], v[36:37], off offset:16
	global_load_dwordx2 v[120:121], v[36:37], off offset:32
	global_load_dwordx2 v[122:123], v[36:37], off offset:48
	global_load_dwordx2 v[124:125], v[36:37], off offset:64
	global_load_dwordx2 v[126:127], v[36:37], off offset:80
	global_load_dwordx2 v[128:129], v[36:37], off offset:96
	global_load_dwordx2 v[130:131], v[36:37], off offset:112
	v_or_b32_e32 v0, s2, v43
	v_lshl_add_u64 v[34:35], v[0:1], 2, s[14:15]
	global_load_dword v0, v[34:35], off
	v_lshl_add_u64 v[34:35], v[50:51], 0, s[82:83]
	s_add_i32 s1, s1, 1
	s_mov_b64 s[2:3], 0x10000
	v_lshl_add_u64 v[52:53], v[52:53], 0, s[2:3]
	s_cmp_eq_u32 s1, 4
	s_waitcnt vmcnt(0)
	v_mov_b32_e32 v38, v116
	v_mov_b32_e32 v39, v117
	v_lshlrev_b32_e32 v40, 16, v38
	v_and_b32_e32 v41, 0xffff0000, v38
	v_mul_f32_e32 v38, 0x3d372713, v40
	v_mul_f32_e32 v38, v38, v40
	v_mov_b32_e32 v54, v40
	v_fmac_f32_e32 v54, v38, v54
	v_mul_f32_e32 v38, 0x3f4c422a, v54
	v_add_f32_e32 v38, v38, v38
	v_mul_f32_e32 v38, 0xbfb8aa3b, v38
	v_exp_f32_e32 v38, v38
	v_mov_b32_e32 v55, v41
	s_waitcnt vmcnt(0)
	v_pk_add_f32 v[18:19], v[18:19], v[0:1] op_sel_hi:[1,0]
	v_pk_add_f32 v[20:21], v[20:21], v[0:1] op_sel_hi:[1,0]
	v_add_f32_e32 v38, 1.0, v38
	v_rcp_f32_e32 v54, v38
	v_mul_f32_e32 v38, 0x3d372713, v41
	v_mul_f32_e32 v38, v38, v41
	v_fmac_f32_e32 v55, v38, v55
	v_mul_f32_e32 v38, 0x3f4c422a, v55
	v_add_f32_e32 v38, v38, v38
	v_mul_f32_e32 v38, 0xbfb8aa3b, v38
	v_exp_f32_e32 v38, v38
	v_pk_add_f32 v[22:23], v[22:23], v[0:1] op_sel_hi:[1,0]
	v_pk_add_f32 v[2:3], v[2:3], v[0:1] op_sel_hi:[1,0]
	v_pk_add_f32 v[4:5], v[4:5], v[0:1] op_sel_hi:[1,0]
	v_add_f32_e32 v38, 1.0, v38
	v_rcp_f32_e32 v55, v38
	v_lshlrev_b32_e32 v38, 16, v39
	v_and_b32_e32 v39, 0xffff0000, v39
	v_pk_add_f32 v[6:7], v[6:7], v[0:1] op_sel_hi:[1,0]
	v_pk_mul_f32 v[40:41], v[54:55], v[40:41]
	v_mov_b32_e32 v54, v39
	v_pk_mul_f32 v[18:19], v[18:19], v[40:41]
	v_mul_f32_e32 v40, 0x3d372713, v38
	v_mul_f32_e32 v40, v40, v38
	v_mov_b32_e32 v41, v38
	v_fmac_f32_e32 v41, v40, v41
	v_mul_f32_e32 v40, 0x3f4c422a, v41
	v_mul_f32_e32 v41, 0x3d372713, v39
	v_mul_f32_e32 v41, v41, v39
	v_fmac_f32_e32 v54, v41, v54
	v_mul_f32_e32 v41, 0x3f4c422a, v54
	v_add_f32_e32 v40, v40, v40
	v_add_f32_e32 v41, v41, v41
	v_mul_f32_e32 v40, 0xbfb8aa3b, v40
	v_mul_f32_e32 v41, 0xbfb8aa3b, v41
	v_exp_f32_e32 v40, v40
	v_exp_f32_e32 v41, v41
	v_cvt_pk_bf16_f32 v18, v18, v19
	v_add_f32_e32 v40, 1.0, v40
	v_add_f32_e32 v41, 1.0, v41
	v_rcp_f32_e32 v40, v40
	v_rcp_f32_e32 v41, v41
	s_nop 0
	v_pk_mul_f32 v[38:39], v[40:41], v[38:39]
	s_nop 0
	v_pk_mul_f32 v[20:21], v[20:21], v[38:39]
	s_nop 0
	v_cvt_pk_bf16_f32 v19, v20, v21
	global_store_dwordx2 v[34:35], v[18:19], off
	v_mov_b32_e32 v18, v118
	v_mov_b32_e32 v19, v119
	v_lshlrev_b32_e32 v20, 16, v18
	v_and_b32_e32 v21, 0xffff0000, v18
	v_mul_f32_e32 v18, 0x3d372713, v20
	v_mul_f32_e32 v18, v18, v20
	v_mov_b32_e32 v38, v20
	v_fmac_f32_e32 v38, v18, v38
	v_mul_f32_e32 v18, 0x3f4c422a, v38
	v_add_f32_e32 v18, v18, v18
	v_mul_f32_e32 v18, 0xbfb8aa3b, v18
	v_exp_f32_e32 v18, v18
	v_mov_b32_e32 v39, v21
	v_add_f32_e32 v18, 1.0, v18
	v_rcp_f32_e32 v38, v18
	v_mul_f32_e32 v18, 0x3d372713, v21
	v_mul_f32_e32 v18, v18, v21
	v_fmac_f32_e32 v39, v18, v39
	v_mul_f32_e32 v18, 0x3f4c422a, v39
	v_add_f32_e32 v18, v18, v18
	v_mul_f32_e32 v18, 0xbfb8aa3b, v18
	v_exp_f32_e32 v18, v18
	s_nop 0
	v_add_f32_e32 v18, 1.0, v18
	v_rcp_f32_e32 v39, v18
	v_lshlrev_b32_e32 v18, 16, v19
	v_and_b32_e32 v19, 0xffff0000, v19
	v_pk_mul_f32 v[20:21], v[38:39], v[20:21]
	s_nop 0
	v_pk_mul_f32 v[20:21], v[22:23], v[20:21]
	v_mul_f32_e32 v22, 0x3d372713, v18
	v_mul_f32_e32 v22, v22, v18
	v_mov_b32_e32 v23, v18
	v_fmac_f32_e32 v23, v22, v23
	v_mul_f32_e32 v22, 0x3f4c422a, v23
	v_mul_f32_e32 v23, 0x3d372713, v19
	v_mul_f32_e32 v23, v23, v19
	v_mov_b32_e32 v38, v19
	v_fmac_f32_e32 v38, v23, v38
	v_mul_f32_e32 v23, 0x3f4c422a, v38
	v_add_f32_e32 v22, v22, v22
	v_add_f32_e32 v23, v23, v23
	v_mul_f32_e32 v22, 0xbfb8aa3b, v22
	v_mul_f32_e32 v23, 0xbfb8aa3b, v23
	v_exp_f32_e32 v22, v22
	v_exp_f32_e32 v23, v23
	v_cvt_pk_bf16_f32 v20, v20, v21
	v_add_f32_e32 v22, 1.0, v22
	v_add_f32_e32 v23, 1.0, v23
	v_rcp_f32_e32 v22, v22
	v_rcp_f32_e32 v23, v23
	s_nop 0
	v_pk_mul_f32 v[18:19], v[22:23], v[18:19]
	v_pk_add_f32 v[22:23], v[24:25], v[0:1] op_sel_hi:[1,0]
; __device__ __forceinline__ unsigned cvtpk(float lo, float hi) { f32x2_t v = {lo, hi}; bf16x2_t b = __builtin_convertvector(v, bf16x2_t); return __builtin_bit_cast(unsigned, b); }
; __device__ __forceinline__ float bflo(unsigned u) { return __uint_as_float(u << 16); }
; __device__ __forceinline__ float bfhi(unsigned u) { return __uint_as_float(u & 0xffff0000u); }
; __device__ __forceinline__ float geluf_(float x) { const float y = 0.7978845608028654f * (x + 0.044715f * x * x * x); return x * sigmoidf_(2.0f * y); }
; __device__ __forceinline__ void sgu_item(LAS unsigned char* lds, const bf16* PROJ, bf16* MIX, const float* lg, const float* lb, const float* ws_, const float* bs_, int item, int tid) {
;     ...
;             for (int g4 = 0; g4 < 4; ++g4) { const u32x2 uw = *(const u32x2*)(up + 32 * ct + 8 * g4);
;                 const float o0 = geluf_(bflo(uw.x)) * (acc[ct][4 * g4] + bias), o1 = geluf_(bfhi(uw.x)) * (acc[ct][4 * g4 + 1] + bias), o2 = geluf_(bflo(uw.y)) * (acc[ct][4 * g4 + 2] + bias), o3 = geluf_(bfhi(uw.y)) * (acc[ct][4 * g4 + 3] + bias);
;                 u32x2 w; w.x = cvtpk(o0, o1); w.y = cvtpk(o2, o3); *(u32x2*)(op + 32 * ct + 8 * g4) = w; } }
	s_nop 0
	v_pk_mul_f32 v[18:19], v[22:23], v[18:19]
	s_nop 0
	v_cvt_pk_bf16_f32 v21, v18, v19
	v_mov_b32_e32 v18, v120
	v_mov_b32_e32 v19, v121
	s_nop 0
	global_store_dwordx2 v[34:35], v[20:21], off offset:16
	v_lshlrev_b32_e32 v20, 16, v18
	v_and_b32_e32 v21, 0xffff0000, v18
	v_mul_f32_e32 v18, 0x3d372713, v20
	v_mul_f32_e32 v18, v18, v20
	v_mov_b32_e32 v22, v20
	v_fmac_f32_e32 v22, v18, v22
	v_mul_f32_e32 v18, 0x3f4c422a, v22
	v_add_f32_e32 v18, v18, v18
	v_mul_f32_e32 v18, 0xbfb8aa3b, v18
	v_exp_f32_e32 v18, v18
	v_mov_b32_e32 v23, v21
	v_add_f32_e32 v18, 1.0, v18
	v_rcp_f32_e32 v22, v18
	v_mul_f32_e32 v18, 0x3d372713, v21
	v_mul_f32_e32 v18, v18, v21
	v_fmac_f32_e32 v23, v18, v23
	v_mul_f32_e32 v18, 0x3f4c422a, v23
	v_add_f32_e32 v18, v18, v18
	v_mul_f32_e32 v18, 0xbfb8aa3b, v18
	v_exp_f32_e32 v18, v18
	s_nop 0
	v_add_f32_e32 v18, 1.0, v18
	v_rcp_f32_e32 v23, v18
	v_lshlrev_b32_e32 v18, 16, v19
	v_and_b32_e32 v19, 0xffff0000, v19
	v_mov_b32_e32 v24, v19
	v_pk_mul_f32 v[20:21], v[22:23], v[20:21]
	v_pk_add_f32 v[22:23], v[26:27], v[0:1] op_sel_hi:[1,0]
	s_nop 0
	v_pk_mul_f32 v[20:21], v[22:23], v[20:21]
	v_mul_f32_e32 v22, 0x3d372713, v18
	v_mul_f32_e32 v22, v22, v18
	v_mov_b32_e32 v23, v18
	v_fmac_f32_e32 v23, v22, v23
	v_mul_f32_e32 v22, 0x3f4c422a, v23
	v_mul_f32_e32 v23, 0x3d372713, v19
	v_mul_f32_e32 v23, v23, v19
	v_fmac_f32_e32 v24, v23, v24
	v_mul_f32_e32 v23, 0x3f4c422a, v24
	v_add_f32_e32 v22, v22, v22
	v_add_f32_e32 v23, v23, v23
	v_mul_f32_e32 v22, 0xbfb8aa3b, v22
	v_mul_f32_e32 v23, 0xbfb8aa3b, v23
	v_exp_f32_e32 v22, v22
	v_exp_f32_e32 v23, v23
	v_cvt_pk_bf16_f32 v20, v20, v21
	v_add_f32_e32 v22, 1.0, v22
	v_add_f32_e32 v23, 1.0, v23
	v_rcp_f32_e32 v22, v22
	v_rcp_f32_e32 v23, v23
	s_nop 0
	v_pk_mul_f32 v[18:19], v[22:23], v[18:19]
	v_pk_add_f32 v[22:23], v[28:29], v[0:1] op_sel_hi:[1,0]
	s_nop 0
	v_pk_mul_f32 v[18:19], v[22:23], v[18:19]
	s_nop 0
	v_cvt_pk_bf16_f32 v21, v18, v19
	v_mov_b32_e32 v18, v122
	v_mov_b32_e32 v19, v123
	s_nop 0
	global_store_dwordx2 v[34:35], v[20:21], off offset:32
	v_lshlrev_b32_e32 v20, 16, v18
	v_and_b32_e32 v21, 0xffff0000, v18
	v_mul_f32_e32 v18, 0x3d372713, v20
	v_mul_f32_e32 v18, v18, v20
	v_mov_b32_e32 v22, v20
	v_fmac_f32_e32 v22, v18, v22
	v_mul_f32_e32 v18, 0x3f4c422a, v22
	v_add_f32_e32 v18, v18, v18
	v_mul_f32_e32 v18, 0xbfb8aa3b, v18
	v_exp_f32_e32 v18, v18
	v_mov_b32_e32 v23, v21
	v_add_f32_e32 v18, 1.0, v18
	v_rcp_f32_e32 v22, v18
	v_mul_f32_e32 v18, 0x3d372713, v21
	v_mul_f32_e32 v18, v18, v21
	v_fmac_f32_e32 v23, v18, v23
	v_mul_f32_e32 v18, 0x3f4c422a, v23
	v_add_f32_e32 v18, v18, v18
	v_mul_f32_e32 v18, 0xbfb8aa3b, v18
	v_exp_f32_e32 v18, v18
	s_nop 0
	v_add_f32_e32 v18, 1.0, v18
	v_rcp_f32_e32 v23, v18
	v_lshlrev_b32_e32 v18, 16, v19
	v_and_b32_e32 v19, 0xffff0000, v19
	v_mov_b32_e32 v24, v19
	v_pk_mul_f32 v[20:21], v[22:23], v[20:21]
	v_pk_add_f32 v[22:23], v[30:31], v[0:1] op_sel_hi:[1,0]
	s_nop 0
	v_pk_mul_f32 v[20:21], v[22:23], v[20:21]
	v_mul_f32_e32 v22, 0x3d372713, v18
	v_mul_f32_e32 v22, v22, v18
	v_mov_b32_e32 v23, v18
	v_fmac_f32_e32 v23, v22, v23
	v_mul_f32_e32 v22, 0x3f4c422a, v23
	v_mul_f32_e32 v23, 0x3d372713, v19
	v_mul_f32_e32 v23, v23, v19
	v_fmac_f32_e32 v24, v23, v24
	v_mul_f32_e32 v23, 0x3f4c422a, v24
	v_add_f32_e32 v22, v22, v22
	v_add_f32_e32 v23, v23, v23
	v_mul_f32_e32 v22, 0xbfb8aa3b, v22
	v_mul_f32_e32 v23, 0xbfb8aa3b, v23
	v_exp_f32_e32 v22, v22
	v_exp_f32_e32 v23, v23
	v_cvt_pk_bf16_f32 v20, v20, v21
	v_add_f32_e32 v22, 1.0, v22
	v_add_f32_e32 v23, 1.0, v23
	v_rcp_f32_e32 v22, v22
	v_rcp_f32_e32 v23, v23
	s_nop 0
	v_pk_mul_f32 v[18:19], v[22:23], v[18:19]
	v_pk_add_f32 v[22:23], v[32:33], v[0:1] op_sel_hi:[1,0]
	s_nop 0
	v_pk_mul_f32 v[18:19], v[22:23], v[18:19]
	s_nop 0
	v_cvt_pk_bf16_f32 v21, v18, v19
	v_mov_b32_e32 v18, v124
	v_mov_b32_e32 v19, v125
	s_nop 0
	global_store_dwordx2 v[34:35], v[20:21], off offset:48
	v_lshlrev_b32_e32 v20, 16, v18
	v_and_b32_e32 v21, 0xffff0000, v18
	v_mul_f32_e32 v18, 0x3d372713, v20
	v_mul_f32_e32 v18, v18, v20
	v_mov_b32_e32 v22, v20
	v_fmac_f32_e32 v22, v18, v22
	v_mul_f32_e32 v18, 0x3f4c422a, v22
	v_add_f32_e32 v18, v18, v18
	v_mul_f32_e32 v18, 0xbfb8aa3b, v18
	v_exp_f32_e32 v18, v18
	v_mov_b32_e32 v23, v21
	v_add_f32_e32 v18, 1.0, v18
	v_rcp_f32_e32 v22, v18
	v_mul_f32_e32 v18, 0x3d372713, v21
	v_mul_f32_e32 v18, v18, v21
	v_fmac_f32_e32 v23, v18, v23
	v_mul_f32_e32 v18, 0x3f4c422a, v23
	v_add_f32_e32 v18, v18, v18
	v_mul_f32_e32 v18, 0xbfb8aa3b, v18
	v_exp_f32_e32 v18, v18
	s_nop 0
	v_add_f32_e32 v18, 1.0, v18
	v_rcp_f32_e32 v23, v18
	v_lshlrev_b32_e32 v18, 16, v19
	v_and_b32_e32 v19, 0xffff0000, v19
	v_pk_mul_f32 v[20:21], v[22:23], v[20:21]
	s_nop 0
	v_pk_mul_f32 v[2:3], v[2:3], v[20:21]
	v_mul_f32_e32 v20, 0x3d372713, v18
	v_mul_f32_e32 v20, v20, v18
	v_mov_b32_e32 v21, v18
	v_fmac_f32_e32 v21, v20, v21
	v_mul_f32_e32 v20, 0x3f4c422a, v21
	v_mul_f32_e32 v21, 0x3d372713, v19
	v_mul_f32_e32 v21, v21, v19
	v_mov_b32_e32 v22, v19
	v_fmac_f32_e32 v22, v21, v22
	v_mul_f32_e32 v21, 0x3f4c422a, v22
	v_add_f32_e32 v20, v20, v20
	v_add_f32_e32 v21, v21, v21
	v_mul_f32_e32 v20, 0xbfb8aa3b, v20
	v_mul_f32_e32 v21, 0xbfb8aa3b, v21
	v_exp_f32_e32 v20, v20
	v_exp_f32_e32 v21, v21
	v_cvt_pk_bf16_f32 v2, v2, v3
	v_add_f32_e32 v20, 1.0, v20
	v_add_f32_e32 v21, 1.0, v21
	v_rcp_f32_e32 v20, v20
; __device__ __forceinline__ unsigned cvtpk(float lo, float hi) { f32x2_t v = {lo, hi}; bf16x2_t b = __builtin_convertvector(v, bf16x2_t); return __builtin_bit_cast(unsigned, b); }
; __device__ __forceinline__ float bflo(unsigned u) { return __uint_as_float(u << 16); }
; __device__ __forceinline__ float bfhi(unsigned u) { return __uint_as_float(u & 0xffff0000u); }
; __device__ __forceinline__ float geluf_(float x) { const float y = 0.7978845608028654f * (x + 0.044715f * x * x * x); return x * sigmoidf_(2.0f * y); }
; __device__ __forceinline__ void sgu_item(LAS unsigned char* lds, const bf16* PROJ, bf16* MIX, const float* lg, const float* lb, const float* ws_, const float* bs_, int item, int tid) {
;     ...
;             for (int g4 = 0; g4 < 4; ++g4) { const u32x2 uw = *(const u32x2*)(up + 32 * ct + 8 * g4);
;                 const float o0 = geluf_(bflo(uw.x)) * (acc[ct][4 * g4] + bias), o1 = geluf_(bfhi(uw.x)) * (acc[ct][4 * g4 + 1] + bias), o2 = geluf_(bflo(uw.y)) * (acc[ct][4 * g4 + 2] + bias), o3 = geluf_(bfhi(uw.y)) * (acc[ct][4 * g4 + 3] + bias);
;                 u32x2 w; w.x = cvtpk(o0, o1); w.y = cvtpk(o2, o3); *(u32x2*)(op + 32 * ct + 8 * g4) = w; } }
;         __syncthreads();
	v_rcp_f32_e32 v21, v21
	s_nop 0
	v_pk_mul_f32 v[18:19], v[20:21], v[18:19]
	s_nop 0
	v_pk_mul_f32 v[4:5], v[4:5], v[18:19]
	s_nop 0
	v_cvt_pk_bf16_f32 v3, v4, v5
	global_store_dwordx2 v[34:35], v[2:3], off offset:64
	v_mov_b32_e32 v2, v126
	v_mov_b32_e32 v3, v127
	v_lshlrev_b32_e32 v4, 16, v2
	v_and_b32_e32 v5, 0xffff0000, v2
	v_mul_f32_e32 v2, 0x3d372713, v4
	v_mul_f32_e32 v2, v2, v4
	v_mov_b32_e32 v18, v4
	v_fmac_f32_e32 v18, v2, v18
	v_mul_f32_e32 v2, 0x3f4c422a, v18
	v_add_f32_e32 v2, v2, v2
	v_mul_f32_e32 v2, 0xbfb8aa3b, v2
	v_exp_f32_e32 v2, v2
	v_mov_b32_e32 v19, v5
	v_add_f32_e32 v2, 1.0, v2
	v_rcp_f32_e32 v18, v2
	v_mul_f32_e32 v2, 0x3d372713, v5
	v_mul_f32_e32 v2, v2, v5
	v_fmac_f32_e32 v19, v2, v19
	v_mul_f32_e32 v2, 0x3f4c422a, v19
	v_add_f32_e32 v2, v2, v2
	v_mul_f32_e32 v2, 0xbfb8aa3b, v2
	v_exp_f32_e32 v2, v2
	s_nop 0
	v_add_f32_e32 v2, 1.0, v2
	v_rcp_f32_e32 v19, v2
	v_lshlrev_b32_e32 v2, 16, v3
	v_and_b32_e32 v3, 0xffff0000, v3
	v_pk_mul_f32 v[4:5], v[18:19], v[4:5]
	s_nop 0
	v_pk_mul_f32 v[4:5], v[6:7], v[4:5]
	v_mul_f32_e32 v6, 0x3d372713, v2
	v_mul_f32_e32 v6, v6, v2
	v_mov_b32_e32 v7, v2
	v_fmac_f32_e32 v7, v6, v7
	v_mul_f32_e32 v6, 0x3f4c422a, v7
	v_mul_f32_e32 v7, 0x3d372713, v3
	v_mul_f32_e32 v7, v7, v3
	v_mov_b32_e32 v18, v3
	v_fmac_f32_e32 v18, v7, v18
	v_mul_f32_e32 v7, 0x3f4c422a, v18
	v_add_f32_e32 v6, v6, v6
	v_add_f32_e32 v7, v7, v7
	v_mul_f32_e32 v6, 0xbfb8aa3b, v6
	v_mul_f32_e32 v7, 0xbfb8aa3b, v7
	v_exp_f32_e32 v6, v6
	v_exp_f32_e32 v7, v7
	v_cvt_pk_bf16_f32 v4, v4, v5
	v_add_f32_e32 v6, 1.0, v6
	v_add_f32_e32 v7, 1.0, v7
	v_rcp_f32_e32 v6, v6
	v_rcp_f32_e32 v7, v7
	s_nop 0
	v_pk_mul_f32 v[2:3], v[6:7], v[2:3]
	v_pk_add_f32 v[6:7], v[8:9], v[0:1] op_sel_hi:[1,0]
	s_nop 0
	v_pk_mul_f32 v[2:3], v[6:7], v[2:3]
	s_nop 0
	v_cvt_pk_bf16_f32 v5, v2, v3
	v_mov_b32_e32 v2, v128
	v_mov_b32_e32 v3, v129
	s_nop 0
	global_store_dwordx2 v[34:35], v[4:5], off offset:80
	v_lshlrev_b32_e32 v4, 16, v2
	v_and_b32_e32 v5, 0xffff0000, v2
	v_mul_f32_e32 v2, 0x3d372713, v4
	v_mul_f32_e32 v2, v2, v4
	v_mov_b32_e32 v6, v4
	v_fmac_f32_e32 v6, v2, v6
	v_mul_f32_e32 v2, 0x3f4c422a, v6
	v_add_f32_e32 v2, v2, v2
	v_mul_f32_e32 v2, 0xbfb8aa3b, v2
	v_exp_f32_e32 v2, v2
	v_mov_b32_e32 v7, v5
	v_add_f32_e32 v2, 1.0, v2
	v_rcp_f32_e32 v6, v2
	v_mul_f32_e32 v2, 0x3d372713, v5
	v_mul_f32_e32 v2, v2, v5
	v_fmac_f32_e32 v7, v2, v7
	v_mul_f32_e32 v2, 0x3f4c422a, v7
	v_add_f32_e32 v2, v2, v2
	v_mul_f32_e32 v2, 0xbfb8aa3b, v2
	v_exp_f32_e32 v2, v2
	s_nop 0
	v_add_f32_e32 v2, 1.0, v2
	v_rcp_f32_e32 v7, v2
	v_lshlrev_b32_e32 v2, 16, v3
	v_and_b32_e32 v3, 0xffff0000, v3
	v_mov_b32_e32 v8, v3
	v_pk_mul_f32 v[4:5], v[6:7], v[4:5]
	v_pk_add_f32 v[6:7], v[10:11], v[0:1] op_sel_hi:[1,0]
	s_nop 0
	v_pk_mul_f32 v[4:5], v[6:7], v[4:5]
	v_mul_f32_e32 v6, 0x3d372713, v2
	v_mul_f32_e32 v6, v6, v2
	v_mov_b32_e32 v7, v2
	v_fmac_f32_e32 v7, v6, v7
	v_mul_f32_e32 v6, 0x3f4c422a, v7
	v_mul_f32_e32 v7, 0x3d372713, v3
	v_mul_f32_e32 v7, v7, v3
	v_fmac_f32_e32 v8, v7, v8
	v_mul_f32_e32 v7, 0x3f4c422a, v8
	v_add_f32_e32 v6, v6, v6
	v_add_f32_e32 v7, v7, v7
	v_mul_f32_e32 v6, 0xbfb8aa3b, v6
	v_mul_f32_e32 v7, 0xbfb8aa3b, v7
	v_exp_f32_e32 v6, v6
	v_exp_f32_e32 v7, v7
	v_cvt_pk_bf16_f32 v4, v4, v5
	v_add_f32_e32 v6, 1.0, v6
	v_add_f32_e32 v7, 1.0, v7
	v_rcp_f32_e32 v6, v6
	v_rcp_f32_e32 v7, v7
	s_nop 0
	v_pk_mul_f32 v[2:3], v[6:7], v[2:3]
	v_pk_add_f32 v[6:7], v[12:13], v[0:1] op_sel_hi:[1,0]
	s_nop 0
	v_pk_mul_f32 v[2:3], v[6:7], v[2:3]
	s_nop 0
	v_cvt_pk_bf16_f32 v5, v2, v3
	v_mov_b32_e32 v2, v130
	v_mov_b32_e32 v3, v131
	s_nop 0
	global_store_dwordx2 v[34:35], v[4:5], off offset:96
	v_lshlrev_b32_e32 v4, 16, v2
	v_and_b32_e32 v5, 0xffff0000, v2
	v_mul_f32_e32 v2, 0x3d372713, v4
	v_mul_f32_e32 v2, v2, v4
	v_mov_b32_e32 v6, v4
	v_fmac_f32_e32 v6, v2, v6
	v_mul_f32_e32 v2, 0x3f4c422a, v6
	v_add_f32_e32 v2, v2, v2
	v_mul_f32_e32 v2, 0xbfb8aa3b, v2
	v_exp_f32_e32 v2, v2
	v_mov_b32_e32 v7, v5
	v_add_f32_e32 v2, 1.0, v2
	v_rcp_f32_e32 v6, v2
	v_mul_f32_e32 v2, 0x3d372713, v5
	v_mul_f32_e32 v2, v2, v5
	v_fmac_f32_e32 v7, v2, v7
	v_mul_f32_e32 v2, 0x3f4c422a, v7
	v_add_f32_e32 v2, v2, v2
	v_mul_f32_e32 v2, 0xbfb8aa3b, v2
	v_exp_f32_e32 v2, v2
	s_nop 0
	v_add_f32_e32 v2, 1.0, v2
	v_rcp_f32_e32 v7, v2
	v_lshlrev_b32_e32 v2, 16, v3
	v_and_b32_e32 v3, 0xffff0000, v3
	v_mov_b32_e32 v8, v3
	v_pk_mul_f32 v[4:5], v[6:7], v[4:5]
	v_pk_add_f32 v[6:7], v[14:15], v[0:1] op_sel_hi:[1,0]
	s_nop 0
	v_pk_mul_f32 v[4:5], v[6:7], v[4:5]
	v_mul_f32_e32 v6, 0x3d372713, v2
	v_mul_f32_e32 v6, v6, v2
	v_mov_b32_e32 v7, v2
	v_fmac_f32_e32 v7, v6, v7
	v_mul_f32_e32 v6, 0x3f4c422a, v7
	v_mul_f32_e32 v7, 0x3d372713, v3
	v_mul_f32_e32 v7, v7, v3
	v_fmac_f32_e32 v8, v7, v8
	v_mul_f32_e32 v7, 0x3f4c422a, v8
	v_add_f32_e32 v6, v6, v6
	v_add_f32_e32 v7, v7, v7
	v_mul_f32_e32 v6, 0xbfb8aa3b, v6
	v_mul_f32_e32 v7, 0xbfb8aa3b, v7
	v_exp_f32_e32 v6, v6
	v_exp_f32_e32 v7, v7
	v_cvt_pk_bf16_f32 v4, v4, v5
	v_add_f32_e32 v6, 1.0, v6
	v_add_f32_e32 v7, 1.0, v7
	v_rcp_f32_e32 v6, v6
	v_rcp_f32_e32 v7, v7
	s_nop 0
	v_pk_mul_f32 v[2:3], v[6:7], v[2:3]
	v_pk_add_f32 v[6:7], v[16:17], v[0:1] op_sel_hi:[1,0]
	s_nop 0
	v_pk_mul_f32 v[2:3], v[6:7], v[2:3]
	s_nop 0
	v_cvt_pk_bf16_f32 v5, v2, v3
	global_store_dwordx2 v[34:35], v[4:5], off offset:112
	s_barrier
	s_cbranch_scc0 .LBB0_363

; #define LAS __attribute__((address_space(3)))
; __device__ __forceinline__ void moba_unit(LAS unsigned char* lds, const bf16* PROJ, bf16* MIX, int b, int h, int j, int tid) {
;     const int lane = tid & 63, wid = __builtin_amdgcn_readfirstlane(tid >> 6), r32 = lane & 31, hi = lane >> 5;
;     const size_t rowbase = (size_t)b * SEQ; const int q0 = 256 * j;
;     const bf16* Kg = PROJ + rowbase * NPROJ + 512 + h * 64; const bf16* Vg = PROJ + rowbase * NPROJ + 1024 + h * 64;
;     const bf16* Qp = PROJ + (rowbase + q0 + 32 * wid + r32) * NPROJ + h * 64;
;     bf16x8 qr[4];
; #pragma unroll
;     for (int d0 = 0; d0 < 4; ++d0) qr[d0] = *(const bf16x8*)(Qp + 16 * d0 + 8 * hi);
;     u32x4 kr, vr, kr1, vr1; tile_load(Kg, Vg, q0, tid, kr, vr); tile_load(Kg, Vg, q0 + 64, tid, kr1, vr1);
;     LAS float* km = (LAS float*)(lds + OFF_KM); LAS float* part = (LAS float*)(lds + OFF_PART);
;     { const int ch = tid & 7, rr = tid >> 3;
;       for (int n = 0; n < j; ++n) { float a[8];
; #pragma unroll
;         for (int e = 0; e < 8; ++e) a[e] = 0.f;
; #pragma unroll
;         for (int i = 0; i < 4; ++i) { const u32x4 v = *(const u32x4*)(Kg + (size_t)(256 * n + rr + 64 * i) * NPROJ + ch * 8);
.LBB0_441:
	s_and_b64 vcc, exec, s[0:1]
	s_cbranch_vccz .LBB0_320
	s_ashr_i32 s7, s24, 6
	s_sub_i32 s5, 7, s7
	s_bfe_u32 s0, s24, 0x30003
	s_lshl_b32 s1, s0, 11
	s_lshl_b32 s4, s5, 8
	s_mul_i32 s10, s0, 0xa00000
	v_readfirstlane_b32 s11, v200
	s_add_u32 s2, s84, s10
	s_addc_u32 s3, s85, 0
	s_ashr_i32 s6, s11, 1
	s_lshl_b32 s0, s24, 6
	s_andn2_b32 s6, s6, 31
	s_and_b32 s8, s0, 0x1c0
	s_add_i32 s0, s4, s1
	s_ashr_i32 s1, s6, 31
	v_and_b32_e32 v67, 31, v200
	s_add_u32 s0, s6, s0
	v_or_b32_e32 v166, s0, v67
	v_mov_b64_e32 v[2:3], s[84:85]
	s_addc_u32 s9, s1, 0
	v_mad_u64_u32 v[2:3], s[0:1], v166, s40, v[2:3]
	s_lshl_b32 s82, s8, 1
	v_bfe_u32 v66, v200, 5, 1
	v_mad_i32_i24 v3, s9, v233, v3
	s_add_u32 s0, s2, s82
	v_ashrrev_i32_e32 v173, 3, v200
	v_lshl_add_u64 v[2:3], v[2:3], 0, s[82:83]
	v_lshlrev_b32_e32 v168, 4, v66
	v_mov_b32_e32 v169, v1
	s_addc_u32 s1, s3, 0
	v_add_u32_e32 v50, s4, v173
	v_lshlrev_b32_e32 v0, 3, v200
	v_lshl_add_u64 v[2:3], v[2:3], 0, v[168:169]
	v_mov_b64_e32 v[10:11], s[0:1]
	v_and_b32_e32 v0, 56, v0
	v_add_u32_e32 v12, 64, v50
	global_load_dwordx4 v[142:145], v[2:3], off
	global_load_dwordx4 v[138:141], v[2:3], off offset:32
	global_load_dwordx4 v[134:137], v[2:3], off offset:64
	global_load_dwordx4 v[130:133], v[2:3], off offset:96
	v_mad_i64_i32 v[2:3], s[2:3], v50, s40, v[10:11]
	v_lshlrev_b32_e32 v0, 1, v0
	v_mad_i64_i32 v[10:11], s[2:3], v12, s40, v[10:11]
	v_lshl_add_u64 v[6:7], v[2:3], 0, v[0:1]
	v_lshl_add_u64 v[14:15], v[10:11], 0, v[0:1]
	global_load_dwordx4 v[2:5], v[6:7], off offset:1024
	s_nop 0
	global_load_dwordx4 v[6:9], v[6:7], off offset:2048
	s_nop 0
	global_load_dwordx4 v[10:13], v[14:15], off offset:1024
	s_nop 0
	global_load_dwordx4 v[14:17], v[14:15], off offset:2048
	v_and_b32_e32 v68, 63, v200
	s_cmp_lg_u32 s7, 7
	v_lshlrev_b32_e32 v18, 2, v68
	v_mov_b32_e32 v167, s9
	s_cselect_b64 s[2:3], -1, 0
	s_cmp_eq_u32 s7, 7
	v_xor_b32_e32 v169, 0x80, v18
	s_cbranch_scc1 .LBB0_447
	s_lshl_b32 s11, s11, 2
	s_and_b32 s11, s11, 0xffffff00
	s_add_i32 s11, s11, 0
	s_add_i32 s11, s11, 0xe000
	v_lshl_add_u32 v38, v68, 5, s11
	s_and_b32 s11, s24, 7
	s_add_i32 s12, s7, -7
	s_lshl_b32 s11, s11, 7
	s_add_u32 s10, s11, s10
	s_addc_u32 s11, 0, 0
	v_xor_b32_e32 v36, 32, v18
	v_xor_b32_e32 v37, 64, v18
	v_mov_b64_e32 v[18:19], s[10:11]
	v_mad_i64_i32 v[18:19], s[10:11], v173, s40, v[18:19]
	v_and_b32_e32 v20, 7, v200
	v_lshlrev_b32_e32 v20, 4, v20
	v_mov_b32_e32 v21, v1
	v_readlane_b32 s10, v255, 28
	v_lshl_add_u64 v[18:19], v[18:19], 0, v[20:21]
	v_readlane_b32 s11, v255, 29
	v_cmp_gt_u32_e64 s[8:9], 8, v68
	v_mov_b32_e32 v39, s12
	v_lshl_add_u64 v[18:19], s[10:11], 0, v[18:19]
	s_mov_b64 s[100:101], 0x140000
	global_load_dwordx4 v[100:103], v[18:19], off
	v_add_co_u32_e32 v118, vcc, 0xfff10000, v18
	s_nop 1
	v_addc_co_u32_e32 v119, vcc, -1, v19, vcc
	global_load_dwordx4 v[104:107], v[118:119], off
	v_add_co_u32_e32 v118, vcc, 0xfff60000, v18
	s_nop 1
	v_addc_co_u32_e32 v119, vcc, -1, v19, vcc
	global_load_dwordx4 v[108:111], v[118:119], off
	v_add_co_u32_e32 v118, vcc, 0xfffb0000, v18
	s_nop 1
	v_addc_co_u32_e32 v119, vcc, -1, v19, vcc
	global_load_dwordx4 v[112:115], v[118:119], off
	s_branch .LBB0_445

; __device__ __forceinline__ float bflo(unsigned u) { return __uint_as_float(u << 16); }
; __device__ __forceinline__ float bfhi(unsigned u) { return __uint_as_float(u & 0xffff0000u); }
; __device__ __forceinline__ float shx(float v, int o, int lane) { return __builtin_bit_cast(float, __builtin_amdgcn_ds_bpermute((lane ^ o) << 2, __builtin_bit_cast(int, v))); }
; __device__ __forceinline__ void moba_unit(LAS unsigned char* lds, const bf16* PROJ, bf16* MIX, int b, int h, int j, int tid) {
;     ...
;     { const int ch = tid & 7, rr = tid >> 3;
;       for (int n = 0; n < j; ++n) { float a[8];
; #pragma unroll
;         for (int e = 0; e < 8; ++e) a[e] = 0.f;
; #pragma unroll
;         for (int i = 0; i < 4; ++i) { const u32x4 v = *(const u32x4*)(Kg + (size_t)(256 * n + rr + 64 * i) * NPROJ + ch * 8);
;             a[0] += bflo(v.x); a[1] += bfhi(v.x); a[2] += bflo(v.y); a[3] += bfhi(v.y); a[4] += bflo(v.z); a[5] += bfhi(v.z); a[6] += bflo(v.w); a[7] += bfhi(v.w); }
; #pragma unroll
;         for (int e = 0; e < 8; ++e) { a[e] += shx(a[e], 8, lane); a[e] += shx(a[e], 16, lane); a[e] += shx(a[e], 32, lane); }
;         if (lane < 8) {
; #pragma unroll
;             for (int e = 0; e < 8; ++e) part[(n * 8 + wid) * 64 + lane * 8 + e] = a[e]; } }
;       __syncthreads();
.LBB0_445:
	s_waitcnt vmcnt(0) lgkmcnt(0)
	v_mov_b32_e32 v20, v100
	v_mov_b32_e32 v21, v101
	v_mov_b32_e32 v22, v102
	v_mov_b32_e32 v23, v103
	v_mov_b32_e32 v24, v104
	v_mov_b32_e32 v25, v105
	v_mov_b32_e32 v26, v106
	v_mov_b32_e32 v27, v107
	v_mov_b32_e32 v28, v108
	v_mov_b32_e32 v29, v109
	v_mov_b32_e32 v30, v110
	v_mov_b32_e32 v31, v111
	v_mov_b32_e32 v32, v112
	v_mov_b32_e32 v33, v113
	v_mov_b32_e32 v34, v114
	v_mov_b32_e32 v35, v115
	v_lshl_add_u64 v[116:117], v[18:19], 0, s[100:101]
	global_load_dwordx4 v[100:103], v[116:117], off
	v_add_co_u32_e32 v118, vcc, 0xfff10000, v116
	s_nop 1
	v_addc_co_u32_e32 v119, vcc, -1, v117, vcc
	global_load_dwordx4 v[104:107], v[118:119], off
	v_add_co_u32_e32 v118, vcc, 0xfff60000, v116
	s_nop 1
	v_addc_co_u32_e32 v119, vcc, -1, v117, vcc
	global_load_dwordx4 v[108:111], v[118:119], off
	v_add_co_u32_e32 v118, vcc, 0xfffb0000, v116
	s_nop 1
	v_addc_co_u32_e32 v119, vcc, -1, v117, vcc
	global_load_dwordx4 v[112:115], v[118:119], off
	v_lshlrev_b32_e32 v40, 16, v20
	v_and_b32_e32 v41, 0xffff0000, v20
	v_lshlrev_b32_e32 v20, 16, v21
	v_and_b32_e32 v21, 0xffff0000, v21
	v_lshlrev_b32_e32 v42, 16, v22
	v_lshlrev_b32_e32 v44, 16, v24
	v_and_b32_e32 v45, 0xffff0000, v24
	v_lshlrev_b32_e32 v24, 16, v25
	v_and_b32_e32 v25, 0xffff0000, v25
	v_lshlrev_b32_e32 v46, 16, v26
	v_and_b32_e32 v47, 0xffff0000, v26
	v_lshlrev_b32_e32 v26, 16, v27
	v_and_b32_e32 v27, 0xffff0000, v27
	v_pk_add_f32 v[44:45], v[44:45], 0 op_sel_hi:[1,0]
	v_lshlrev_b32_e32 v48, 16, v28
	v_and_b32_e32 v49, 0xffff0000, v28
	v_pk_add_f32 v[24:25], v[24:25], 0 op_sel_hi:[1,0]
	v_lshlrev_b32_e32 v28, 16, v29
	v_and_b32_e32 v29, 0xffff0000, v29
	v_pk_add_f32 v[46:47], v[46:47], 0 op_sel_hi:[1,0]
	v_lshlrev_b32_e32 v52, 16, v30
	v_and_b32_e32 v53, 0xffff0000, v30
	v_pk_add_f32 v[26:27], v[26:27], 0 op_sel_hi:[1,0]
	v_lshlrev_b32_e32 v30, 16, v31
	v_and_b32_e32 v31, 0xffff0000, v31
	v_pk_add_f32 v[44:45], v[44:45], v[48:49]
	v_lshlrev_b32_e32 v48, 16, v32
	v_and_b32_e32 v49, 0xffff0000, v32
	v_pk_add_f32 v[24:25], v[24:25], v[28:29]
	v_lshlrev_b32_e32 v28, 16, v33
	v_and_b32_e32 v29, 0xffff0000, v33
	v_pk_add_f32 v[32:33], v[46:47], v[52:53]
	v_lshlrev_b32_e32 v46, 16, v34
	v_and_b32_e32 v47, 0xffff0000, v34
	v_pk_add_f32 v[26:27], v[26:27], v[30:31]
	v_lshlrev_b32_e32 v30, 16, v35
	v_and_b32_e32 v31, 0xffff0000, v35
	v_and_b32_e32 v43, 0xffff0000, v22
	v_lshlrev_b32_e32 v22, 16, v23
	v_and_b32_e32 v23, 0xffff0000, v23
	v_pk_add_f32 v[34:35], v[44:45], v[48:49]
	v_pk_add_f32 v[24:25], v[24:25], v[28:29]
	v_pk_add_f32 v[28:29], v[32:33], v[46:47]
	v_pk_add_f32 v[26:27], v[26:27], v[30:31]
	v_pk_add_f32 v[30:31], v[34:35], v[40:41]
	v_pk_add_f32 v[20:21], v[24:25], v[20:21]
	v_pk_add_f32 v[24:25], v[28:29], v[42:43]
	v_pk_add_f32 v[22:23], v[26:27], v[22:23]
	ds_bpermute_b32 v26, v36, v30
	ds_bpermute_b32 v27, v36, v31
	ds_bpermute_b32 v28, v36, v20
	ds_bpermute_b32 v29, v36, v21
	ds_bpermute_b32 v32, v36, v24
	ds_bpermute_b32 v33, v36, v25
	ds_bpermute_b32 v34, v36, v22
	ds_bpermute_b32 v35, v36, v23
	s_waitcnt lgkmcnt(6)
	v_pk_add_f32 v[26:27], v[30:31], v[26:27]
	s_waitcnt lgkmcnt(4)
	v_pk_add_f32 v[20:21], v[20:21], v[28:29]
	s_waitcnt lgkmcnt(2)
	v_pk_add_f32 v[28:29], v[24:25], v[32:33]
	ds_bpermute_b32 v24, v37, v26
	s_waitcnt lgkmcnt(1)
	v_pk_add_f32 v[22:23], v[22:23], v[34:35]
	ds_bpermute_b32 v25, v37, v27
	ds_bpermute_b32 v30, v37, v20
	ds_bpermute_b32 v31, v37, v21
	ds_bpermute_b32 v32, v37, v28
	ds_bpermute_b32 v33, v37, v29
	ds_bpermute_b32 v34, v37, v22
	ds_bpermute_b32 v35, v37, v23
	s_waitcnt lgkmcnt(6)
	v_pk_add_f32 v[24:25], v[26:27], v[24:25]
	s_waitcnt lgkmcnt(4)
	v_pk_add_f32 v[26:27], v[20:21], v[30:31]
	s_waitcnt lgkmcnt(2)
	v_pk_add_f32 v[20:21], v[28:29], v[32:33]
	ds_bpermute_b32 v32, v169, v24
	s_waitcnt lgkmcnt(1)
	v_pk_add_f32 v[22:23], v[22:23], v[34:35]
	ds_bpermute_b32 v33, v169, v25
	ds_bpermute_b32 v34, v169, v26
	ds_bpermute_b32 v35, v169, v27
	ds_bpermute_b32 v28, v169, v20
	ds_bpermute_b32 v29, v169, v21
	ds_bpermute_b32 v30, v169, v22
	ds_bpermute_b32 v31, v169, v23
	s_and_saveexec_b64 s[10:11], s[8:9]
	s_cbranch_execz .LBB0_444
	s_waitcnt lgkmcnt(6)
	v_pk_add_f32 v[24:25], v[24:25], v[32:33]
	s_waitcnt lgkmcnt(4)
	v_pk_add_f32 v[26:27], v[26:27], v[34:35]
	s_waitcnt lgkmcnt(2)
	v_pk_add_f32 v[20:21], v[20:21], v[28:29]
	s_waitcnt lgkmcnt(0)
	v_pk_add_f32 v[22:23], v[22:23], v[30:31]
	ds_write_b128 v38, v[24:27]
	ds_write_b128 v38, v[20:23] offset:16
	s_branch .LBB0_444
.LBB0_447:
	s_waitcnt vmcnt(0)
	v_cmp_gt_i32_e32 vcc, 64, v200
	s_waitcnt lgkmcnt(0)
	s_barrier
	s_and_saveexec_b64 s[8:9], vcc
	s_cbranch_execz .LBB0_451
	s_andn2_b64 vcc, exec, s[2:3]
	s_cbranch_vccnz .LBB0_451
	v_lshlrev_b32_e32 v19, 2, v200
	v_readlane_b32 s3, v255, 0
	s_add_i32 s2, s7, -7
	v_mov_b32_e32 v20, s2
	v_add_u32_e32 v18, s3, v19
	s_add_i32 s3, 0, 0xe000
	v_add_u32_e32 v19, s3, v19
